# v060 + G1 and FU units issue the LDS reads of their first load segment at the top of the unit loop, ahead of the scheduler/pointer set-up chain (read latency overlaps the chain)
# speedup vs baseline: 1.0058x; 1.0010x over previous
;     __host__ __device__ bool next(int i, Unit& u) const {
;         const long L = (long)i * G + c; if (L >= nwg) return false;
;         int wgid = (int)L; { const int q = nwg / NXCD, r = nwg % NXCD, xcd = wgid % NXCD, off = wgid / NXCD; wgid = (xcd < r ? xcd * (q + 1) : r * (q + 1) + (xcd - r) * q) + off; }
;         if (ORD_TR > 0) {
;             const int nig = ORD_TR * nM, gid = wgid / nig, fn = gid * ORD_TR, gsz = (nN - fn) < ORD_TR ? (nN - fn) : ORD_TR;
;             u.pn = fn + ((wgid % nig) % gsz); u.pm = (wgid % nig) / gsz; u.kt0 = 0; u.nkt = nkt; u.slab = -1; u.krot = 0; return true; }
;         const int nig = WGM * nN, gid = wgid / nig, fm = gid * WGM, gsz = (nM - fm) < WGM ? (nM - fm) : WGM;
;         u.pm = fm + ((wgid % nig) % gsz); u.pn = (wgid % nig) / gsz; u.kt0 = 0; u.nkt = nkt; u.slab = -1; u.krot = KROT ? 2 * (((c & 7) * (nkt >> 1)) >> 3) : 0; return true;
.LBB0_267:
	v_add_u32_e32 v148, 0x10000, v221
	v_add_u32_e32 v164, 0x14000, v221
	ds_read_b128 v[136:139], v148
	ds_read_b128 v[140:143], v148 offset:1024
	ds_read_b128 v[144:147], v148 offset:2048
	ds_read_b128 v[148:151], v148 offset:3072
	ds_read_b128 v[152:155], v164
	ds_read_b128 v[156:159], v164 offset:1024
	ds_read_b128 v[160:163], v164 offset:2048
	ds_read_b128 v[164:167], v164 offset:3072
	ds_read_b128 v[192:195], v222
	ds_read_b128 v[196:199], v222 offset:1024
	ds_read_b128 v[200:203], v222 offset:2048
	ds_read_b128 v[224:227], v222 offset:3072
	ds_read_b128 v[228:231], v222 offset:4096
	ds_read_b128 v[232:235], v222 offset:5120
	ds_read_b128 v[236:239], v222 offset:6144
	ds_read_b128 v[240:243], v222 offset:7168
	s_add_i32 s94, s94, 1
	v_readlane_b32 s0, v251, 56
	s_mul_i32 s0, s94, s0
	s_mul_hi_u32 s1, s94, s68
	s_add_i32 s1, s1, s0
	s_mul_i32 s0, s94, s68
	s_add_u32 s42, s0, s92
	v_readlane_b32 s0, v251, 55
	s_addc_u32 s43, s1, s0
	v_mov_b64_e32 v[2:3], 0x3a8
	v_cmp_gt_i64_e32 vcc, s[42:43], v[170:171]
	v_cmp_lt_i64_e64 s[26:27], s[42:43], v[2:3]
	s_cbranch_vccnz .LBB0_269
	s_ashr_i32 s0, s42, 31
	s_lshr_b32 s0, s0, 29
	s_add_i32 s0, s42, s0
	s_ashr_i32 s1, s0, 3
	s_and_b32 s0, s0, -8
	s_sub_i32 s0, s42, s0
	s_cmp_lt_i32 s0, 0
	s_movk_i32 s4, 0x76
	s_cselect_b32 s29, s4, 0x75
	s_mul_i32 s0, s0, s29
	s_add_i32 s0, s0, s1
	s_mul_hi_i32 s1, s0, 0xd20d20d3
	s_add_i32 s1, s1, s0
	s_lshr_b32 s29, s1, 31
	s_ashr_i32 s1, s1, 7
	s_add_i32 s1, s1, s29
	s_mul_i32 s29, s1, 6
	s_sub_i32 s42, 36, s29
	s_min_i32 s42, s42, 6
	s_abs_i32 s43, s42
	v_cvt_f32_u32_e32 v2, s43
	s_sub_i32 s47, 0, s43
	s_mulk_i32 s1, 0x9c
	s_sub_i32 s0, s0, s1
	v_rcp_iflag_f32_e32 v2, v2
	s_abs_i32 s1, s0
	s_xor_b32 s46, s0, s42
	s_ashr_i32 s46, s46, 31
	v_mul_f32_e32 v2, 0x4f7ffffe, v2
	v_cvt_u32_f32_e32 v2, v2
	s_nop 0
	v_readfirstlane_b32 s48, v2
	s_mul_i32 s47, s47, s48
	s_mul_hi_u32 s47, s48, s47
	s_add_i32 s48, s48, s47
	s_mul_hi_u32 s47, s1, s48
	s_mul_i32 s48, s47, s43
	s_sub_i32 s1, s1, s48
	s_add_i32 s49, s47, 1
	s_sub_i32 s48, s1, s43
	s_cmp_ge_u32 s1, s43
	s_cselect_b32 s47, s49, s47
	s_cselect_b32 s1, s48, s1
	s_add_i32 s48, s47, 1
	s_cmp_ge_u32 s1, s43
	s_cselect_b32 s1, s48, s47
	s_xor_b32 s1, s1, s46
	s_sub_i32 s34, s1, s46
	s_mul_i32 s1, s34, s42
	s_sub_i32 s0, s0, s1
	s_add_i32 s28, s29, s0

; #define PG8_STAGE(bufoff, gbase, voff) do { _Pragma("unroll") for (int _i = 0; _i < 2; ++_i) \
;         __builtin_amdgcn_global_load_lds((const unsigned*)((const char*)(gbase) + (voff)[_i]), (PG8_LAS unsigned*)(lds + (bufoff) + ldsw + _i * 8192), 16, 0, AUX_A); } while (0)
; #define PG8_STAGEB(bufoff, gbase, voff) do { _Pragma("unroll") for (int _i = 0; _i < 2; ++_i) \
;         __builtin_amdgcn_global_load_lds((const unsigned*)((const char*)(gbase) + (voff)[_i]), (PG8_LAS unsigned*)(lds + (bufoff) + ldsw + _i * 8192), 16, 0, AUX_B); } while (0)
; #define PG8_LDA(dst, b, h) do { _Pragma("unroll") for (int m = 0; m < 4; ++m) _Pragma("unroll") for (int k = 0; k < 2; ++k) dst[m][k] = *(const PG8_LAS bf16x8*)(lds + PG8_SA(b, h) + aoff + m * 2048 + k * 1024); } while (0)
; #define PG8_LDB(dst, b, h) do { _Pragma("unroll") for (int n = 0; n < 2; ++n) _Pragma("unroll") for (int k = 0; k < 2; ++k) dst[n][k] = *(const PG8_LAS bf16x8*)(lds + PG8_SB(b, h) + boff + n * 2048 + k * 1024); } while (0)
; #define PG8_BAR __builtin_amdgcn_s_barrier()
; template <class Epi, class Sched, bool ALIGN_EPI = false, bool SP2 = false>
; __device__ __forceinline__ void gemm_phase(PG8_LAS unsigned char* lds, const Gemm g, const Sched& S, const Epi& E) {
;     ...
;         const char* nAr = has_next ? nA + (size_t)nxt.krot * kstep : PG8_KP(cA, 0, rot, nt); const char* nBr = has_next ? nB + (size_t)nxt.krot * kstep : PG8_KP(cB, 0, rot, nt);
;         for (int t = 0; t < nt; t += 2) {
;             const bool last = (t == nt - 2);
;             const char* a1 = PG8_KP(cA, t + 1, rot, nt);
;             const char* a2 = last ? nAr : PG8_KP(cA, t + 2, rot, nt); const char* b2 = last ? nBr : PG8_KP(cB, t + 2, rot, nt);
;             const char* a3 = a2 + kstep; const char* b3 = b2 + kstep;
;             if (last && has_next) S.a_ready(nxt);
;             if constexpr (SP2) {
;             PG8_LDB(B0, 0, 0); PG8_LDB(B1, 0, 1); PG8_SCHED; PG8_LDA(At, 0, 0); PG8_STAGE(PG8_SA(1, 1), a1 + hstep, voffA);
;             PG8_WAIT_V(8); PG8_WAIT_L(0); PG8_BAR; PG8_MMA(0, 0, At, B0); PG8_MMA(0, 1, At, B1); PG8_BAR; PG8_SCHED;
;             PG8_LDA(At, 0, 1); PG8_STAGEB(PG8_SB(0, 0), b2, voffB); PG8_STAGEB(PG8_SB(0, 1), b2 + hstep, voffB); PG8_STAGE(PG8_SA(0, 0), a2, voffA);
;             PG8_WAIT_V(8); PG8_WAIT_L(0); PG8_BAR; PG8_MMA(1, 0, At, B0); PG8_MMA(1, 1, At, B1); PG8_BAR; PG8_SCHED;
.Lrp_270:
.Lpk_270:
	s_add_i32 s81, s29, 2
	s_cmp_lt_u32 s29, 30
	s_cselect_b32 s0, 0, 0xffffffe0
	s_add_i32 s0, s81, s0
	s_ashr_i32 s1, s0, 31
	s_lshl_b64 s[0:1], s[0:1], 7
	s_add_u32 s42, s40, s0
	s_addc_u32 s43, s41, s1
	s_add_u32 s0, s38, s0
	s_addc_u32 s1, s39, s1
	s_cmp_eq_u32 s29, 30
	s_cselect_b32 s59, s49, s43
	s_cselect_b32 s58, s51, s42
	s_cselect_b32 s61, vcc_lo, s1
	s_cselect_b32 s60, vcc_hi, s0
	s_add_i32 s43, 0, 0x10000
	s_add_i32 s97, s43, s70
	s_add_i32 s46, 0, 0x14000
	s_add_i32 m0, s96, 0xc000
	s_add_i32 s69, s96, 0xe000
	s_add_i32 s84, s97, 0x2000
	s_add_u32 s62, s60, 0x80000
	s_addc_u32 s63, s61, 0
	s_add_i32 s4, s46, s70
	s_add_i32 s5, s4, 0x2000
	s_add_i32 s1, 0, 0x18000
	s_add_i32 s47, 0, 0x1c000
	s_add_u32 s56, s58, 0x80000
	s_addc_u32 s57, s59, 0
	s_add_i32 s0, s1, s70
	s_add_i32 s89, s0, 0x2000
	s_add_u32 s42, s60, 0x80080
	s_addc_u32 s43, s61, 0
	s_add_i32 s46, s47, s70
	s_add_i32 s92, s46, 0x2000
	s_cmp_gt_u32 s29, 29
	global_load_lds_dwordx4 v[134:135], off
	s_mov_b32 m0, s69
	s_nop 0
	global_load_lds_dwordx4 v[132:133], off
	s_waitcnt vmcnt(8)
	s_waitcnt lgkmcnt(0)
	s_setprio 1
	s_barrier
	v_mfma_f32_16x16x32_bf16 v[128:131], v[136:139], v[192:195], 0
	v_mfma_f32_16x16x32_bf16 v[128:131], v[140:143], v[196:199], v[128:131]
	v_mfma_f32_16x16x32_bf16 v[124:127], v[144:147], v[192:195], 0
	v_mfma_f32_16x16x32_bf16 v[124:127], v[148:151], v[196:199], v[124:127]
	v_mfma_f32_16x16x32_bf16 v[112:115], v[136:139], v[200:203], 0
	v_mfma_f32_16x16x32_bf16 v[112:115], v[140:143], v[224:227], v[112:115]
	v_mfma_f32_16x16x32_bf16 v[108:111], v[144:147], v[200:203], 0
	v_mfma_f32_16x16x32_bf16 v[108:111], v[148:151], v[224:227], v[108:111]
	v_mfma_f32_16x16x32_bf16 v[94:97], v[136:139], v[228:231], 0
	v_mfma_f32_16x16x32_bf16 v[94:97], v[140:143], v[232:235], v[94:97]
	v_mfma_f32_16x16x32_bf16 v[90:93], v[144:147], v[228:231], 0
	v_mfma_f32_16x16x32_bf16 v[90:93], v[148:151], v[232:235], v[90:93]
	v_mfma_f32_16x16x32_bf16 v[78:81], v[136:139], v[236:239], 0
	v_mfma_f32_16x16x32_bf16 v[78:81], v[140:143], v[240:243], v[78:81]
	v_mfma_f32_16x16x32_bf16 v[74:77], v[144:147], v[236:239], 0
	v_mfma_f32_16x16x32_bf16 v[74:77], v[148:151], v[240:243], v[74:77]
	s_setprio 0
	s_setprio 1
	v_mfma_f32_16x16x32_bf16 v[120:123], v[152:155], v[192:195], 0
	v_mfma_f32_16x16x32_bf16 v[120:123], v[156:159], v[196:199], v[120:123]
	v_mfma_f32_16x16x32_bf16 v[116:119], v[160:163], v[192:195], 0
	v_mfma_f32_16x16x32_bf16 v[116:119], v[164:167], v[196:199], v[116:119]
	v_mfma_f32_16x16x32_bf16 v[104:107], v[152:155], v[200:203], 0
	v_mfma_f32_16x16x32_bf16 v[104:107], v[156:159], v[224:227], v[104:107]
	v_mfma_f32_16x16x32_bf16 v[100:103], v[160:163], v[200:203], 0
	v_mfma_f32_16x16x32_bf16 v[100:103], v[164:167], v[224:227], v[100:103]
	v_mfma_f32_16x16x32_bf16 v[86:89], v[152:155], v[228:231], 0
	v_mfma_f32_16x16x32_bf16 v[86:89], v[156:159], v[232:235], v[86:89]
	v_mfma_f32_16x16x32_bf16 v[82:85], v[160:163], v[228:231], 0
	v_mfma_f32_16x16x32_bf16 v[82:85], v[164:167], v[232:235], v[82:85]
	v_mfma_f32_16x16x32_bf16 v[70:73], v[152:155], v[236:239], 0
	v_mfma_f32_16x16x32_bf16 v[70:73], v[156:159], v[240:243], v[70:73]
	s_setprio 2
	s_barrier
	v_mfma_f32_16x16x32_bf16 v[66:69], v[160:163], v[236:239], 0
	v_mfma_f32_16x16x32_bf16 v[66:69], v[164:167], v[240:243], v[66:69]
	s_setprio 0
	s_mov_b32 m0, s97
	v_lshl_add_u64 v[244:245], s[60:61], 0, v[184:185]
	ds_read_b128 v[192:195], v222 offset:16384
	ds_read_b128 v[196:199], v222 offset:17408
	ds_read_b128 v[200:203], v222 offset:18432
	ds_read_b128 v[224:227], v222 offset:19456
	ds_read_b128 v[228:231], v222 offset:20480
	ds_read_b128 v[232:235], v222 offset:21504
	ds_read_b128 v[236:239], v222 offset:22528
	ds_read_b128 v[240:243], v222 offset:23552
	global_load_lds_dwordx4 v[244:245], off
	v_lshl_add_u64 v[246:247], s[60:61], 0, v[180:181]
	s_mov_b32 m0, s84
	v_lshl_add_u64 v[212:213], s[62:63], 0, v[184:185]
	global_load_lds_dwordx4 v[246:247], off
	s_mov_b32 m0, s4
	v_lshl_add_u64 v[172:173], s[58:59], 0, v[182:183]
	global_load_lds_dwordx4 v[212:213], off
	v_lshl_add_u64 v[212:213], s[62:63], 0, v[180:181]
	s_mov_b32 m0, s5
	s_nop 0
	global_load_lds_dwordx4 v[212:213], off
	v_lshl_add_u64 v[212:213], s[58:59], 0, v[186:187]
	s_mov_b32 m0, s96
	s_nop 0
	global_load_lds_dwordx4 v[212:213], off
	s_mov_b32 m0, s71
	s_nop 0
	global_load_lds_dwordx4 v[172:173], off
	s_waitcnt vmcnt(8)
	s_waitcnt lgkmcnt(0)
	s_setprio 1
	s_barrier
	v_mfma_f32_16x16x32_bf16 v[62:65], v[136:139], v[192:195], 0
	v_mfma_f32_16x16x32_bf16 v[62:65], v[140:143], v[196:199], v[62:65]
	v_mfma_f32_16x16x32_bf16 v[58:61], v[144:147], v[192:195], 0
	v_mfma_f32_16x16x32_bf16 v[58:61], v[148:151], v[196:199], v[58:61]
	v_mfma_f32_16x16x32_bf16 v[46:49], v[136:139], v[200:203], 0
	v_mfma_f32_16x16x32_bf16 v[46:49], v[140:143], v[224:227], v[46:49]
	v_mfma_f32_16x16x32_bf16 v[42:45], v[144:147], v[200:203], 0
	v_mfma_f32_16x16x32_bf16 v[42:45], v[148:151], v[224:227], v[42:45]
	v_mfma_f32_16x16x32_bf16 v[30:33], v[136:139], v[228:231], 0
	v_mfma_f32_16x16x32_bf16 v[30:33], v[140:143], v[232:235], v[30:33]
	v_mfma_f32_16x16x32_bf16 v[26:29], v[144:147], v[228:231], 0
	v_mfma_f32_16x16x32_bf16 v[26:29], v[148:151], v[232:235], v[26:29]
	v_mfma_f32_16x16x32_bf16 v[14:17], v[136:139], v[236:239], 0
	v_mfma_f32_16x16x32_bf16 v[14:17], v[140:143], v[240:243], v[14:17]
	v_mfma_f32_16x16x32_bf16 v[10:13], v[144:147], v[236:239], 0
	v_mfma_f32_16x16x32_bf16 v[10:13], v[148:151], v[240:243], v[10:13]
	s_setprio 0
	s_setprio 1
	v_mfma_f32_16x16x32_bf16 v[54:57], v[152:155], v[192:195], 0
	v_mfma_f32_16x16x32_bf16 v[54:57], v[156:159], v[196:199], v[54:57]
	v_mfma_f32_16x16x32_bf16 v[50:53], v[160:163], v[192:195], 0
	v_mfma_f32_16x16x32_bf16 v[50:53], v[164:167], v[196:199], v[50:53]
	v_mfma_f32_16x16x32_bf16 v[38:41], v[152:155], v[200:203], 0
	v_mfma_f32_16x16x32_bf16 v[38:41], v[156:159], v[224:227], v[38:41]
	v_mfma_f32_16x16x32_bf16 v[34:37], v[160:163], v[200:203], 0
	v_mfma_f32_16x16x32_bf16 v[34:37], v[164:167], v[224:227], v[34:37]
	v_mfma_f32_16x16x32_bf16 v[22:25], v[152:155], v[228:231], 0
	v_mfma_f32_16x16x32_bf16 v[22:25], v[156:159], v[232:235], v[22:25]
	v_mfma_f32_16x16x32_bf16 v[18:21], v[160:163], v[228:231], 0
	v_mfma_f32_16x16x32_bf16 v[18:21], v[164:167], v[232:235], v[18:21]
	v_mfma_f32_16x16x32_bf16 v[6:9], v[152:155], v[236:239], 0
	v_mfma_f32_16x16x32_bf16 v[6:9], v[156:159], v[240:243], v[6:9]
	s_setprio 2
	s_barrier
; #define PG8_STAGE(bufoff, gbase, voff) do { _Pragma("unroll") for (int _i = 0; _i < 2; ++_i) \
;         __builtin_amdgcn_global_load_lds((const unsigned*)((const char*)(gbase) + (voff)[_i]), (PG8_LAS unsigned*)(lds + (bufoff) + ldsw + _i * 8192), 16, 0, AUX_A); } while (0)
; #define PG8_STAGEB(bufoff, gbase, voff) do { _Pragma("unroll") for (int _i = 0; _i < 2; ++_i) \
;         __builtin_amdgcn_global_load_lds((const unsigned*)((const char*)(gbase) + (voff)[_i]), (PG8_LAS unsigned*)(lds + (bufoff) + ldsw + _i * 8192), 16, 0, AUX_B); } while (0)
; #define PG8_LDA(dst, b, h) do { _Pragma("unroll") for (int m = 0; m < 4; ++m) _Pragma("unroll") for (int k = 0; k < 2; ++k) dst[m][k] = *(const PG8_LAS bf16x8*)(lds + PG8_SA(b, h) + aoff + m * 2048 + k * 1024); } while (0)
; #define PG8_LDB(dst, b, h) do { _Pragma("unroll") for (int n = 0; n < 2; ++n) _Pragma("unroll") for (int k = 0; k < 2; ++k) dst[n][k] = *(const PG8_LAS bf16x8*)(lds + PG8_SB(b, h) + boff + n * 2048 + k * 1024); } while (0)
; #define PG8_MMA(ai, bj, At, Bt) do { __builtin_amdgcn_s_setprio(1); _Pragma("unroll") for (int m = 0; m < 4; ++m) _Pragma("unroll") for (int n = 0; n < 2; ++n) _Pragma("unroll") for (int k = 0; k < 2; ++k) \
;         acc[ai][bj][m][n] = __builtin_amdgcn_mfma_f32_16x16x32_bf16(Bt[n][k], At[m][k], acc[ai][bj][m][n], 0, 0, 0); __builtin_amdgcn_s_setprio(0); } while (0)
; template <class Epi, class Sched, bool ALIGN_EPI = false, bool SP2 = false>
; __device__ __forceinline__ void gemm_phase(PG8_LAS unsigned char* lds, const Gemm g, const Sched& S, const Epi& E) {
;     ...
;             PG8_LDA(At, 0, 1); PG8_STAGEB(PG8_SB(0, 0), b2, voffB); PG8_STAGEB(PG8_SB(0, 1), b2 + hstep, voffB); PG8_STAGE(PG8_SA(0, 0), a2, voffA);
;             PG8_WAIT_V(8); PG8_WAIT_L(0); PG8_BAR; PG8_MMA(1, 0, At, B0); PG8_MMA(1, 1, At, B1); PG8_BAR; PG8_SCHED;
;             PG8_LDB(B0, 1, 0); PG8_LDB(B1, 1, 1); PG8_SCHED; PG8_LDA(At, 1, 0); PG8_STAGE(PG8_SA(0, 1), a2 + hstep, voffA);
;             PG8_WAIT_V(8); PG8_WAIT_L(0); PG8_BAR; PG8_MMA(0, 0, At, B0); PG8_MMA(0, 1, At, B1); PG8_BAR; PG8_SCHED;
;             PG8_LDA(At, 1, 1); PG8_STAGEB(PG8_SB(1, 0), b3, voffB); PG8_STAGEB(PG8_SB(1, 1), b3 + hstep, voffB); PG8_STAGE(PG8_SA(1, 0), a3, voffA);
;             PG8_WAIT_V(8); PG8_WAIT_L(0); PG8_BAR; PG8_MMA(1, 0, At, B0); PG8_MMA(1, 1, At, B1); PG8_BAR; PG8_SCHED;
	v_mfma_f32_16x16x32_bf16 v[2:5], v[160:163], v[236:239], 0
	v_mfma_f32_16x16x32_bf16 v[2:5], v[164:167], v[240:243], v[2:5]
	s_setprio 0
	v_add_u32_e32 v148, s1, v221
	v_add_u32_e32 v164, s47, v221
	ds_read_b128 v[136:139], v148
	ds_read_b128 v[140:143], v148 offset:1024
	ds_read_b128 v[144:147], v148 offset:2048
	ds_read_b128 v[148:151], v148 offset:3072
	ds_read_b128 v[152:155], v164
	ds_read_b128 v[156:159], v164 offset:1024
	ds_read_b128 v[160:163], v164 offset:2048
	ds_read_b128 v[164:167], v164 offset:3072
	s_mov_b32 m0, s33
	v_lshl_add_u64 v[168:169], s[56:57], 0, v[186:187]
	ds_read_b128 v[192:195], v222 offset:32768
	ds_read_b128 v[196:199], v222 offset:33792
	ds_read_b128 v[200:203], v222 offset:34816
	ds_read_b128 v[224:227], v222 offset:35840
	ds_read_b128 v[228:231], v222 offset:36864
	ds_read_b128 v[232:235], v222 offset:37888
	ds_read_b128 v[236:239], v222 offset:38912
	ds_read_b128 v[240:243], v222 offset:39936
	global_load_lds_dwordx4 v[168:169], off
	v_lshl_add_u64 v[168:169], s[56:57], 0, v[182:183]
	s_mov_b32 m0, s30
	s_nop 0
	global_load_lds_dwordx4 v[168:169], off
	s_waitcnt vmcnt(8)
	s_waitcnt lgkmcnt(0)
	s_setprio 1
	s_barrier
	v_mfma_f32_16x16x32_bf16 v[128:131], v[136:139], v[192:195], v[128:131]
	v_mfma_f32_16x16x32_bf16 v[128:131], v[140:143], v[196:199], v[128:131]
	v_mfma_f32_16x16x32_bf16 v[124:127], v[144:147], v[192:195], v[124:127]
	v_mfma_f32_16x16x32_bf16 v[124:127], v[148:151], v[196:199], v[124:127]
	v_mfma_f32_16x16x32_bf16 v[112:115], v[136:139], v[200:203], v[112:115]
	v_mfma_f32_16x16x32_bf16 v[112:115], v[140:143], v[224:227], v[112:115]
	v_mfma_f32_16x16x32_bf16 v[108:111], v[144:147], v[200:203], v[108:111]
	v_mfma_f32_16x16x32_bf16 v[108:111], v[148:151], v[224:227], v[108:111]
	v_mfma_f32_16x16x32_bf16 v[94:97], v[136:139], v[228:231], v[94:97]
	v_mfma_f32_16x16x32_bf16 v[94:97], v[140:143], v[232:235], v[94:97]
	v_mfma_f32_16x16x32_bf16 v[90:93], v[144:147], v[228:231], v[90:93]
	v_mfma_f32_16x16x32_bf16 v[90:93], v[148:151], v[232:235], v[90:93]
	v_mfma_f32_16x16x32_bf16 v[78:81], v[136:139], v[236:239], v[78:81]
	v_mfma_f32_16x16x32_bf16 v[78:81], v[140:143], v[240:243], v[78:81]
	v_mfma_f32_16x16x32_bf16 v[74:77], v[144:147], v[236:239], v[74:77]
	v_mfma_f32_16x16x32_bf16 v[74:77], v[148:151], v[240:243], v[74:77]
	s_setprio 0
	s_setprio 1
	v_mfma_f32_16x16x32_bf16 v[120:123], v[152:155], v[192:195], v[120:123]
	v_mfma_f32_16x16x32_bf16 v[120:123], v[156:159], v[196:199], v[120:123]
	v_mfma_f32_16x16x32_bf16 v[116:119], v[160:163], v[192:195], v[116:119]
	v_mfma_f32_16x16x32_bf16 v[116:119], v[164:167], v[196:199], v[116:119]
	v_mfma_f32_16x16x32_bf16 v[104:107], v[152:155], v[200:203], v[104:107]
	v_mfma_f32_16x16x32_bf16 v[104:107], v[156:159], v[224:227], v[104:107]
	v_mfma_f32_16x16x32_bf16 v[100:103], v[160:163], v[200:203], v[100:103]
	v_mfma_f32_16x16x32_bf16 v[100:103], v[164:167], v[224:227], v[100:103]
	v_mfma_f32_16x16x32_bf16 v[86:89], v[152:155], v[228:231], v[86:89]
	v_mfma_f32_16x16x32_bf16 v[86:89], v[156:159], v[232:235], v[86:89]
	v_mfma_f32_16x16x32_bf16 v[82:85], v[160:163], v[228:231], v[82:85]
	v_mfma_f32_16x16x32_bf16 v[82:85], v[164:167], v[232:235], v[82:85]
	v_mfma_f32_16x16x32_bf16 v[70:73], v[152:155], v[236:239], v[70:73]
	v_mfma_f32_16x16x32_bf16 v[70:73], v[156:159], v[240:243], v[70:73]
	s_setprio 2
	s_barrier
	v_mfma_f32_16x16x32_bf16 v[66:69], v[160:163], v[236:239], v[66:69]
	v_mfma_f32_16x16x32_bf16 v[66:69], v[164:167], v[240:243], v[66:69]
	s_setprio 0
	s_mov_b32 m0, s0
	v_lshl_add_u64 v[168:169], v[244:245], 0, s[76:77]
	ds_read_b128 v[192:195], v222 offset:49152
	ds_read_b128 v[196:199], v222 offset:50176
	ds_read_b128 v[200:203], v222 offset:51200
	ds_read_b128 v[224:227], v222 offset:52224
	ds_read_b128 v[228:231], v222 offset:53248
	ds_read_b128 v[232:235], v222 offset:54272
	ds_read_b128 v[236:239], v222 offset:55296
	ds_read_b128 v[240:243], v222 offset:56320
	global_load_lds_dwordx4 v[168:169], off
	v_lshl_add_u64 v[168:169], v[246:247], 0, s[76:77]
	s_mov_b32 m0, s89
	s_nop 0
	global_load_lds_dwordx4 v[168:169], off
	v_lshl_add_u64 v[168:169], s[42:43], 0, v[184:185]
	s_mov_b32 m0, s46
	s_nop 0
	global_load_lds_dwordx4 v[168:169], off
	v_lshl_add_u64 v[168:169], s[42:43], 0, v[180:181]
	s_mov_b32 m0, s92
	s_nop 0
	global_load_lds_dwordx4 v[168:169], off
	v_lshl_add_u64 v[168:169], v[212:213], 0, s[76:77]
	s_mov_b32 m0, s90
	s_nop 0
	global_load_lds_dwordx4 v[168:169], off
	v_lshl_add_u64 v[168:169], v[172:173], 0, s[76:77]
	s_mov_b32 m0, s91
	s_nop 0
	global_load_lds_dwordx4 v[168:169], off
	s_waitcnt vmcnt(8)
	s_waitcnt lgkmcnt(0)
	s_setprio 1
	s_barrier
	v_mfma_f32_16x16x32_bf16 v[62:65], v[136:139], v[192:195], v[62:65]
	v_mfma_f32_16x16x32_bf16 v[62:65], v[140:143], v[196:199], v[62:65]
	v_mfma_f32_16x16x32_bf16 v[58:61], v[144:147], v[192:195], v[58:61]
	v_mfma_f32_16x16x32_bf16 v[58:61], v[148:151], v[196:199], v[58:61]
	v_mfma_f32_16x16x32_bf16 v[46:49], v[136:139], v[200:203], v[46:49]
	v_mfma_f32_16x16x32_bf16 v[46:49], v[140:143], v[224:227], v[46:49]
	v_mfma_f32_16x16x32_bf16 v[42:45], v[144:147], v[200:203], v[42:45]
	v_mfma_f32_16x16x32_bf16 v[42:45], v[148:151], v[224:227], v[42:45]
	v_mfma_f32_16x16x32_bf16 v[30:33], v[136:139], v[228:231], v[30:33]
	v_mfma_f32_16x16x32_bf16 v[30:33], v[140:143], v[232:235], v[30:33]
	v_mfma_f32_16x16x32_bf16 v[26:29], v[144:147], v[228:231], v[26:29]
	v_mfma_f32_16x16x32_bf16 v[26:29], v[148:151], v[232:235], v[26:29]
	v_mfma_f32_16x16x32_bf16 v[14:17], v[136:139], v[236:239], v[14:17]
	v_mfma_f32_16x16x32_bf16 v[14:17], v[140:143], v[240:243], v[14:17]
	v_mfma_f32_16x16x32_bf16 v[10:13], v[144:147], v[236:239], v[10:13]
	v_mfma_f32_16x16x32_bf16 v[10:13], v[148:151], v[240:243], v[10:13]
	s_setprio 0
	s_setprio 1
	v_mfma_f32_16x16x32_bf16 v[54:57], v[152:155], v[192:195], v[54:57]
	v_mfma_f32_16x16x32_bf16 v[54:57], v[156:159], v[196:199], v[54:57]
	v_mfma_f32_16x16x32_bf16 v[50:53], v[160:163], v[192:195], v[50:53]
	v_mfma_f32_16x16x32_bf16 v[50:53], v[164:167], v[196:199], v[50:53]
	v_mfma_f32_16x16x32_bf16 v[38:41], v[152:155], v[200:203], v[38:41]
	v_mfma_f32_16x16x32_bf16 v[38:41], v[156:159], v[224:227], v[38:41]
	v_mfma_f32_16x16x32_bf16 v[34:37], v[160:163], v[200:203], v[34:37]
	v_mfma_f32_16x16x32_bf16 v[34:37], v[164:167], v[224:227], v[34:37]
	v_mfma_f32_16x16x32_bf16 v[22:25], v[152:155], v[228:231], v[22:25]
	v_mfma_f32_16x16x32_bf16 v[22:25], v[156:159], v[232:235], v[22:25]
	v_mfma_f32_16x16x32_bf16 v[18:21], v[160:163], v[228:231], v[18:21]
	v_mfma_f32_16x16x32_bf16 v[18:21], v[164:167], v[232:235], v[18:21]
	v_mfma_f32_16x16x32_bf16 v[6:9], v[152:155], v[236:239], v[6:9]
	v_mfma_f32_16x16x32_bf16 v[6:9], v[156:159], v[240:243], v[6:9]
	s_setprio 2
	s_barrier
	v_mfma_f32_16x16x32_bf16 v[2:5], v[160:163], v[236:239], v[2:5]
	v_mfma_f32_16x16x32_bf16 v[2:5], v[164:167], v[240:243], v[2:5]
	s_setprio 0
	v_lshl_add_u64 v[132:133], v[132:133], 0, s[86:87]
	v_lshl_add_u64 v[134:135], v[134:135], 0, s[86:87]
	s_mov_b32 s29, s81
	s_cbranch_scc1 .Lpx_270

;     __host__ __device__ bool next(int i, Unit& u) const {
;         const long L = (long)i * G + c; if (L >= nwg) return false;
;         int wgid = (int)L; { const int q = nwg / NXCD, r = nwg % NXCD, xcd = wgid % NXCD, off = wgid / NXCD; wgid = (xcd < r ? xcd * (q + 1) : r * (q + 1) + (xcd - r) * q) + off; }
;         if (ORD_TR > 0) {
;             const int nig = ORD_TR * nM, gid = wgid / nig, fn = gid * ORD_TR, gsz = (nN - fn) < ORD_TR ? (nN - fn) : ORD_TR;
;             u.pn = fn + ((wgid % nig) % gsz); u.pm = (wgid % nig) / gsz; u.kt0 = 0; u.nkt = nkt; u.slab = -1; u.krot = 0; return true; }
;         const int nig = WGM * nN, gid = wgid / nig, fm = gid * WGM, gsz = (nM - fm) < WGM ? (nM - fm) : WGM;
;         u.pm = fm + ((wgid % nig) % gsz); u.pn = (wgid % nig) / gsz; u.kt0 = 0; u.nkt = nkt; u.slab = -1; u.krot = KROT ? 2 * (((c & 7) * (nkt >> 1)) >> 3) : 0; return true;
.LBB0_1455:
	v_add_u32_e32 v162, 0x10000, v99
	v_add_u32_e32 v166, 0x14000, v99
	ds_read_b128 v[150:153], v162
	ds_read_b128 v[154:157], v162 offset:1024
	ds_read_b128 v[158:161], v162 offset:2048
	ds_read_b128 v[162:165], v162 offset:3072
	ds_read_b128 v[180:183], v166
	ds_read_b128 v[184:187], v166 offset:1024
	ds_read_b128 v[188:191], v166 offset:2048
	ds_read_b128 v[192:195], v166 offset:3072
	ds_read_b128 v[196:199], v149
	ds_read_b128 v[200:203], v149 offset:1024
	ds_read_b128 v[222:225], v149 offset:2048
	ds_read_b128 v[226:229], v149 offset:3072
	ds_read_b128 v[230:233], v149 offset:4096
	ds_read_b128 v[234:237], v149 offset:5120
	ds_read_b128 v[238:241], v149 offset:6144
	ds_read_b128 v[242:245], v149 offset:7168
	s_add_i32 s63, s63, 1
	v_readlane_b32 s0, v251, 56
	s_mul_i32 s0, s63, s0
	s_mul_hi_u32 s1, s63, s68
	s_add_i32 s1, s1, s0
	s_mul_i32 s0, s63, s68
	s_add_u32 s16, s0, s92
	v_readlane_b32 s0, v251, 55
	s_addc_u32 s17, s1, s0
	v_cmp_gt_i64_e32 vcc, s[16:17], v[178:179]
	v_cmp_lt_i64_e64 s[38:39], s[16:17], v[176:177]
	s_cbranch_vccnz .LBB0_1457
	s_ashr_i32 s0, s16, 31
	s_lshr_b32 s0, s0, 29
	s_add_i32 s0, s16, s0
	s_ashr_i32 s1, s0, 3
	s_and_b32 s0, s0, -8
	s_sub_i32 s0, s16, s0
	s_cmp_lt_i32 s0, 0
	s_cselect_b32 s2, s3, 0xc6
	s_mul_i32 s0, s0, s2
	s_add_i32 s0, s0, s1
	s_mul_hi_i32 s1, s0, 0x3e0f83e1
	s_lshr_b32 s2, s1, 31
	s_ashr_i32 s1, s1, 6
	s_add_i32 s1, s1, s2
	s_mul_i32 s2, s1, 6
	s_sub_i32 s12, 36, s2
	s_min_i32 s13, s12, 6
	s_abs_i32 s12, s13
	v_cvt_f32_u32_e32 v2, s12
	s_sub_i32 s15, 0, s12
	s_mulk_i32 s1, 0x108
	s_sub_i32 s0, s0, s1
	v_rcp_iflag_f32_e32 v2, v2
	s_abs_i32 s1, s0
	s_xor_b32 s14, s0, s13
	s_ashr_i32 s14, s14, 31
	v_mul_f32_e32 v2, 0x4f7ffffe, v2
	v_cvt_u32_f32_e32 v2, v2
	s_nop 0
	v_readfirstlane_b32 s16, v2
	s_mul_i32 s15, s15, s16
	s_mul_hi_u32 s15, s16, s15
	s_add_i32 s16, s16, s15
	s_mul_hi_u32 s15, s1, s16
	s_mul_i32 s16, s15, s12
	s_sub_i32 s1, s1, s16
	s_add_i32 s17, s15, 1
	s_sub_i32 s16, s1, s12
	s_cmp_ge_u32 s1, s12
	s_cselect_b32 s15, s17, s15
	s_cselect_b32 s1, s16, s1
	s_add_i32 s16, s15, 1
	s_cmp_ge_u32 s1, s12
	s_cselect_b32 s1, s16, s15
	s_xor_b32 s1, s1, s14
	s_sub_i32 s12, s1, s14
	s_mul_i32 s1, s12, s13
	s_sub_i32 s0, s0, s1
	s_add_i32 s14, s2, s0

; #define PG8_STAGE(bufoff, gbase, voff) do { _Pragma("unroll") for (int _i = 0; _i < 2; ++_i) \
;         __builtin_amdgcn_global_load_lds((const unsigned*)((const char*)(gbase) + (voff)[_i]), (PG8_LAS unsigned*)(lds + (bufoff) + ldsw + _i * 8192), 16, 0, AUX_A); } while (0)
; #define PG8_STAGEB(bufoff, gbase, voff) do { _Pragma("unroll") for (int _i = 0; _i < 2; ++_i) \
;         __builtin_amdgcn_global_load_lds((const unsigned*)((const char*)(gbase) + (voff)[_i]), (PG8_LAS unsigned*)(lds + (bufoff) + ldsw + _i * 8192), 16, 0, AUX_B); } while (0)
; #define PG8_LDA(dst, b, h) do { _Pragma("unroll") for (int m = 0; m < 4; ++m) _Pragma("unroll") for (int k = 0; k < 2; ++k) dst[m][k] = *(const PG8_LAS bf16x8*)(lds + PG8_SA(b, h) + aoff + m * 2048 + k * 1024); } while (0)
; #define PG8_LDB(dst, b, h) do { _Pragma("unroll") for (int n = 0; n < 2; ++n) _Pragma("unroll") for (int k = 0; k < 2; ++k) dst[n][k] = *(const PG8_LAS bf16x8*)(lds + PG8_SB(b, h) + boff + n * 2048 + k * 1024); } while (0)
; #define PG8_BAR __builtin_amdgcn_s_barrier()
; template <class Epi, class Sched, bool ALIGN_EPI = false, bool SP2 = false>
; __device__ __forceinline__ void gemm_phase(PG8_LAS unsigned char* lds, const Gemm g, const Sched& S, const Epi& E) {
;     ...
;         const char* nAr = has_next ? nA + (size_t)nxt.krot * kstep : PG8_KP(cA, 0, rot, nt); const char* nBr = has_next ? nB + (size_t)nxt.krot * kstep : PG8_KP(cB, 0, rot, nt);
;         for (int t = 0; t < nt; t += 2) {
;             const bool last = (t == nt - 2);
;             const char* a1 = PG8_KP(cA, t + 1, rot, nt);
;             const char* a2 = last ? nAr : PG8_KP(cA, t + 2, rot, nt); const char* b2 = last ? nBr : PG8_KP(cB, t + 2, rot, nt);
;             const char* a3 = a2 + kstep; const char* b3 = b2 + kstep;
;             if (last && has_next) S.a_ready(nxt);
;             if constexpr (SP2) {
;             PG8_LDB(B0, 0, 0); PG8_LDB(B1, 0, 1); PG8_SCHED; PG8_LDA(At, 0, 0); PG8_STAGE(PG8_SA(1, 1), a1 + hstep, voffA);
;             PG8_WAIT_V(8); PG8_WAIT_L(0); PG8_BAR; PG8_MMA(0, 0, At, B0); PG8_MMA(0, 1, At, B1); PG8_BAR; PG8_SCHED;
;             PG8_LDA(At, 0, 1); PG8_STAGEB(PG8_SB(0, 0), b2, voffB); PG8_STAGEB(PG8_SB(0, 1), b2 + hstep, voffB); PG8_STAGE(PG8_SA(0, 0), a2, voffA);
;             PG8_WAIT_V(8); PG8_WAIT_L(0); PG8_BAR; PG8_MMA(1, 0, At, B0); PG8_MMA(1, 1, At, B1); PG8_BAR; PG8_SCHED;
.Lrp_1458:
.Lpk_1458:
	s_lshl_b32 s100, s29, 7
	s_add_u32 s100, s40, s100
	s_addc_u32 s101, s41, 0
	s_add_u32 s100, s100, 0x80
	s_addc_u32 s101, s101, 0
	s_add_i32 s30, s29, 2
	s_cmp_lt_u32 s29, 30
	s_cselect_b32 s0, 0, 0xffffffe0
	s_add_i32 s0, s30, s0
	s_ashr_i32 s1, s0, 31
	s_lshl_b64 s[0:1], s[0:1], 7
	s_add_u32 s2, s40, s0
	s_addc_u32 s31, s41, s1
	s_add_u32 s0, s34, s0
	s_addc_u32 s1, s35, s1
	s_cmp_eq_u32 s29, 30
	s_cselect_b32 s45, s13, s31
	s_cselect_b32 s44, s15, s2
	s_cselect_b32 s49, s71, s1
	s_cselect_b32 s48, s75, s0
	s_add_i32 s2, 0, 0x10000
	s_add_i32 s78, s2, s56
	s_add_i32 s31, 0, 0x14000
	s_add_i32 s47, s57, 0xe000
	s_add_i32 s81, s78, 0x2000
	s_add_u32 s50, s48, 0x80000
	s_addc_u32 s51, s49, 0
	s_add_i32 s82, s31, s56
	s_add_i32 s83, s82, 0x2000
	s_add_i32 s84, 0, 0x18000
	s_add_i32 s88, 0, 0x1c000
	s_add_u32 s42, s44, 0x80000
	s_addc_u32 s43, s45, 0
	s_add_i32 s1, s84, s56
	s_add_i32 s0, s1, 0x2000
	s_add_u32 s36, s48, 0x80080
	s_addc_u32 s37, s49, 0
	s_add_i32 s46, s88, s56
	s_add_i32 s31, s46, 0x2000
	v_lshl_add_u64 v[166:167], s[100:101], 0, v[138:139]
	s_mov_b32 m0, s61
	v_lshl_add_u64 v[168:169], s[100:101], 0, v[134:135]
	global_load_lds_dwordx4 v[166:167], off
	s_mov_b32 m0, s62
	s_nop 0
	global_load_lds_dwordx4 v[168:169], off
	s_add_i32 m0, s57, 0xc000
	s_nop 0
	global_load_lds_dwordx4 v[146:147], off
	s_mov_b32 m0, s47
	s_nop 0
	global_load_lds_dwordx4 v[144:145], off
	s_waitcnt vmcnt(8)
	s_waitcnt lgkmcnt(0)
	s_setprio 1
	s_barrier
	v_mfma_f32_16x16x32_bf16 v[128:131], v[150:153], v[196:199], 0
	v_mfma_f32_16x16x32_bf16 v[128:131], v[154:157], v[200:203], v[128:131]
	v_mfma_f32_16x16x32_bf16 v[120:123], v[158:161], v[196:199], 0
	v_mfma_f32_16x16x32_bf16 v[120:123], v[162:165], v[200:203], v[120:123]
	v_mfma_f32_16x16x32_bf16 v[112:115], v[150:153], v[222:225], 0
	v_mfma_f32_16x16x32_bf16 v[112:115], v[154:157], v[226:229], v[112:115]
	v_mfma_f32_16x16x32_bf16 v[104:107], v[158:161], v[222:225], 0
	v_mfma_f32_16x16x32_bf16 v[104:107], v[162:165], v[226:229], v[104:107]
	v_mfma_f32_16x16x32_bf16 v[94:97], v[150:153], v[230:233], 0
	v_mfma_f32_16x16x32_bf16 v[94:97], v[154:157], v[234:237], v[94:97]
	v_mfma_f32_16x16x32_bf16 v[86:89], v[158:161], v[230:233], 0
	v_mfma_f32_16x16x32_bf16 v[86:89], v[162:165], v[234:237], v[86:89]
	v_mfma_f32_16x16x32_bf16 v[78:81], v[150:153], v[238:241], 0
	v_mfma_f32_16x16x32_bf16 v[78:81], v[154:157], v[242:245], v[78:81]
	v_mfma_f32_16x16x32_bf16 v[70:73], v[158:161], v[238:241], 0
	v_mfma_f32_16x16x32_bf16 v[70:73], v[162:165], v[242:245], v[70:73]
	s_setprio 0
	s_setprio 1
	v_mfma_f32_16x16x32_bf16 v[124:127], v[180:183], v[196:199], 0
	v_mfma_f32_16x16x32_bf16 v[124:127], v[184:187], v[200:203], v[124:127]
	v_mfma_f32_16x16x32_bf16 v[116:119], v[188:191], v[196:199], 0
	v_mfma_f32_16x16x32_bf16 v[116:119], v[192:195], v[200:203], v[116:119]
	v_mfma_f32_16x16x32_bf16 v[108:111], v[180:183], v[222:225], 0
	v_mfma_f32_16x16x32_bf16 v[108:111], v[184:187], v[226:229], v[108:111]
	v_mfma_f32_16x16x32_bf16 v[100:103], v[188:191], v[222:225], 0
	v_mfma_f32_16x16x32_bf16 v[100:103], v[192:195], v[226:229], v[100:103]
	v_mfma_f32_16x16x32_bf16 v[90:93], v[180:183], v[230:233], 0
	v_mfma_f32_16x16x32_bf16 v[90:93], v[184:187], v[234:237], v[90:93]
	v_mfma_f32_16x16x32_bf16 v[82:85], v[188:191], v[230:233], 0
	v_mfma_f32_16x16x32_bf16 v[82:85], v[192:195], v[234:237], v[82:85]
	v_mfma_f32_16x16x32_bf16 v[74:77], v[180:183], v[238:241], 0
	v_mfma_f32_16x16x32_bf16 v[74:77], v[184:187], v[242:245], v[74:77]
	s_setprio 2
	s_barrier
	v_mfma_f32_16x16x32_bf16 v[66:69], v[188:191], v[238:241], 0
	v_mfma_f32_16x16x32_bf16 v[66:69], v[192:195], v[242:245], v[66:69]
	s_setprio 0
	s_mov_b32 m0, s78
	v_lshl_add_u64 v[166:167], s[48:49], 0, v[136:137]
	ds_read_b128 v[196:199], v149 offset:16384
	ds_read_b128 v[200:203], v149 offset:17408
	ds_read_b128 v[222:225], v149 offset:18432
	ds_read_b128 v[226:229], v149 offset:19456
	ds_read_b128 v[230:233], v149 offset:20480
	ds_read_b128 v[234:237], v149 offset:21504
	ds_read_b128 v[238:241], v149 offset:22528
	ds_read_b128 v[242:245], v149 offset:23552
	global_load_lds_dwordx4 v[166:167], off
	v_lshl_add_u64 v[168:169], s[48:49], 0, v[132:133]
	s_mov_b32 m0, s81
	v_lshl_add_u64 v[172:173], s[50:51], 0, v[136:137]
	global_load_lds_dwordx4 v[168:169], off
	s_mov_b32 m0, s82
	global_load_lds_dwordx4 v[172:173], off
	v_lshl_add_u64 v[172:173], s[50:51], 0, v[132:133]
	s_mov_b32 m0, s83
	s_nop 0
	global_load_lds_dwordx4 v[172:173], off
	s_waitcnt vmcnt(6)
	s_waitcnt lgkmcnt(0)
	s_setprio 1
	s_barrier
	v_mfma_f32_16x16x32_bf16 v[62:65], v[150:153], v[196:199], 0
	v_mfma_f32_16x16x32_bf16 v[62:65], v[154:157], v[200:203], v[62:65]
	v_mfma_f32_16x16x32_bf16 v[54:57], v[158:161], v[196:199], 0
	v_mfma_f32_16x16x32_bf16 v[54:57], v[162:165], v[200:203], v[54:57]
	v_mfma_f32_16x16x32_bf16 v[46:49], v[150:153], v[222:225], 0
	v_mfma_f32_16x16x32_bf16 v[46:49], v[154:157], v[226:229], v[46:49]
	v_mfma_f32_16x16x32_bf16 v[38:41], v[158:161], v[222:225], 0
	v_mfma_f32_16x16x32_bf16 v[38:41], v[162:165], v[226:229], v[38:41]
	v_mfma_f32_16x16x32_bf16 v[30:33], v[150:153], v[230:233], 0
	v_mfma_f32_16x16x32_bf16 v[30:33], v[154:157], v[234:237], v[30:33]
	v_mfma_f32_16x16x32_bf16 v[22:25], v[158:161], v[230:233], 0
	v_mfma_f32_16x16x32_bf16 v[22:25], v[162:165], v[234:237], v[22:25]
	v_mfma_f32_16x16x32_bf16 v[14:17], v[150:153], v[238:241], 0
	v_mfma_f32_16x16x32_bf16 v[14:17], v[154:157], v[242:245], v[14:17]
	v_mfma_f32_16x16x32_bf16 v[6:9], v[158:161], v[238:241], 0
	v_mfma_f32_16x16x32_bf16 v[6:9], v[162:165], v[242:245], v[6:9]
	s_setprio 0
	s_setprio 1
	v_mfma_f32_16x16x32_bf16 v[58:61], v[180:183], v[196:199], 0
	v_mfma_f32_16x16x32_bf16 v[58:61], v[184:187], v[200:203], v[58:61]
	v_mfma_f32_16x16x32_bf16 v[50:53], v[188:191], v[196:199], 0
	v_mfma_f32_16x16x32_bf16 v[50:53], v[192:195], v[200:203], v[50:53]
	v_mfma_f32_16x16x32_bf16 v[42:45], v[180:183], v[222:225], 0
	v_mfma_f32_16x16x32_bf16 v[42:45], v[184:187], v[226:229], v[42:45]
	v_mfma_f32_16x16x32_bf16 v[34:37], v[188:191], v[222:225], 0
	v_mfma_f32_16x16x32_bf16 v[34:37], v[192:195], v[226:229], v[34:37]
	v_mfma_f32_16x16x32_bf16 v[26:29], v[180:183], v[230:233], 0
	v_mfma_f32_16x16x32_bf16 v[26:29], v[184:187], v[234:237], v[26:29]
	v_mfma_f32_16x16x32_bf16 v[18:21], v[188:191], v[230:233], 0
	v_mfma_f32_16x16x32_bf16 v[18:21], v[192:195], v[234:237], v[18:21]
	v_mfma_f32_16x16x32_bf16 v[10:13], v[180:183], v[238:241], 0
	v_mfma_f32_16x16x32_bf16 v[10:13], v[184:187], v[242:245], v[10:13]
	s_setprio 2
	s_barrier
; #define PG8_STAGE(bufoff, gbase, voff) do { _Pragma("unroll") for (int _i = 0; _i < 2; ++_i) \
;         __builtin_amdgcn_global_load_lds((const unsigned*)((const char*)(gbase) + (voff)[_i]), (PG8_LAS unsigned*)(lds + (bufoff) + ldsw + _i * 8192), 16, 0, AUX_A); } while (0)
; #define PG8_LDA(dst, b, h) do { _Pragma("unroll") for (int m = 0; m < 4; ++m) _Pragma("unroll") for (int k = 0; k < 2; ++k) dst[m][k] = *(const PG8_LAS bf16x8*)(lds + PG8_SA(b, h) + aoff + m * 2048 + k * 1024); } while (0)
; #define PG8_LDB(dst, b, h) do { _Pragma("unroll") for (int n = 0; n < 2; ++n) _Pragma("unroll") for (int k = 0; k < 2; ++k) dst[n][k] = *(const PG8_LAS bf16x8*)(lds + PG8_SB(b, h) + boff + n * 2048 + k * 1024); } while (0)
; #define PG8_MMA(ai, bj, At, Bt) do { __builtin_amdgcn_s_setprio(1); _Pragma("unroll") for (int m = 0; m < 4; ++m) _Pragma("unroll") for (int n = 0; n < 2; ++n) _Pragma("unroll") for (int k = 0; k < 2; ++k) \
;         acc[ai][bj][m][n] = __builtin_amdgcn_mfma_f32_16x16x32_bf16(Bt[n][k], At[m][k], acc[ai][bj][m][n], 0, 0, 0); __builtin_amdgcn_s_setprio(0); } while (0)
; #define PG8_WAIT_V(n) asm volatile("s_waitcnt vmcnt(" #n ")" ::: "memory")
; #define PG8_WAIT_L(n) asm volatile("s_waitcnt lgkmcnt(" #n ")" ::: "memory")
; #define PG8_BAR __builtin_amdgcn_s_barrier()
; #define PG8_SCHED __builtin_amdgcn_sched_barrier(0)
; template <class Epi, class Sched, bool ALIGN_EPI = false, bool SP2 = false>
; __device__ __forceinline__ void gemm_phase(PG8_LAS unsigned char* lds, const Gemm g, const Sched& S, const Epi& E) {
;     ...
;             PG8_LDB(B0, 1, 0); PG8_LDB(B1, 1, 1); PG8_SCHED; PG8_LDA(At, 1, 0); PG8_STAGE(PG8_SA(0, 1), a2 + hstep, voffA);
;             PG8_WAIT_V(8); PG8_WAIT_L(0); PG8_BAR; PG8_MMA(0, 0, At, B0); PG8_MMA(0, 1, At, B1); PG8_BAR; PG8_SCHED;
	v_mfma_f32_16x16x32_bf16 v[2:5], v[188:191], v[238:241], 0
	v_mfma_f32_16x16x32_bf16 v[2:5], v[192:195], v[242:245], v[2:5]
	s_setprio 0
	v_add_u32_e32 v162, s84, v99
	v_add_u32_e32 v192, s88, v99
	ds_read_b128 v[150:153], v162
	ds_read_b128 v[154:157], v162 offset:1024
	ds_read_b128 v[158:161], v162 offset:2048
	ds_read_b128 v[162:165], v162 offset:3072
	ds_read_b128 v[180:183], v192
	ds_read_b128 v[184:187], v192 offset:1024
	ds_read_b128 v[188:191], v192 offset:2048
	ds_read_b128 v[192:195], v192 offset:3072
	s_mov_b32 m0, s59
	v_lshl_add_u64 v[246:247], s[42:43], 0, v[138:139]
	ds_read_b128 v[196:199], v149 offset:32768
	ds_read_b128 v[200:203], v149 offset:33792
	ds_read_b128 v[222:225], v149 offset:34816
	ds_read_b128 v[226:229], v149 offset:35840
	ds_read_b128 v[230:233], v149 offset:36864
	ds_read_b128 v[234:237], v149 offset:37888
	ds_read_b128 v[238:241], v149 offset:38912
	ds_read_b128 v[242:245], v149 offset:39936
	v_lshl_add_u64 v[172:173], s[44:45], 0, v[138:139]
	s_mov_b32 m0, s57
	v_lshl_add_u64 v[212:213], s[44:45], 0, v[134:135]
	global_load_lds_dwordx4 v[172:173], off
	s_mov_b32 m0, s58
	s_nop 0
	global_load_lds_dwordx4 v[212:213], off
	s_mov_b32 m0, s59
	s_nop 0
	global_load_lds_dwordx4 v[246:247], off
	v_lshl_add_u64 v[246:247], s[42:43], 0, v[134:135]
	s_mov_b32 m0, s60
	s_nop 0
	global_load_lds_dwordx4 v[246:247], off
	s_waitcnt vmcnt(8)
	s_waitcnt lgkmcnt(0)
	s_setprio 1
	s_barrier
	v_mfma_f32_16x16x32_bf16 v[128:131], v[150:153], v[196:199], v[128:131]
	v_mfma_f32_16x16x32_bf16 v[128:131], v[154:157], v[200:203], v[128:131]
	v_mfma_f32_16x16x32_bf16 v[120:123], v[158:161], v[196:199], v[120:123]
	v_mfma_f32_16x16x32_bf16 v[120:123], v[162:165], v[200:203], v[120:123]
	v_mfma_f32_16x16x32_bf16 v[112:115], v[150:153], v[222:225], v[112:115]
	v_mfma_f32_16x16x32_bf16 v[112:115], v[154:157], v[226:229], v[112:115]
	v_mfma_f32_16x16x32_bf16 v[104:107], v[158:161], v[222:225], v[104:107]
	v_mfma_f32_16x16x32_bf16 v[104:107], v[162:165], v[226:229], v[104:107]
	v_mfma_f32_16x16x32_bf16 v[94:97], v[150:153], v[230:233], v[94:97]
	v_mfma_f32_16x16x32_bf16 v[94:97], v[154:157], v[234:237], v[94:97]
	v_mfma_f32_16x16x32_bf16 v[86:89], v[158:161], v[230:233], v[86:89]
	v_mfma_f32_16x16x32_bf16 v[86:89], v[162:165], v[234:237], v[86:89]
	v_mfma_f32_16x16x32_bf16 v[78:81], v[150:153], v[238:241], v[78:81]
	v_mfma_f32_16x16x32_bf16 v[78:81], v[154:157], v[242:245], v[78:81]
	v_mfma_f32_16x16x32_bf16 v[70:73], v[158:161], v[238:241], v[70:73]
	v_mfma_f32_16x16x32_bf16 v[70:73], v[162:165], v[242:245], v[70:73]
	s_setprio 0
	s_setprio 1
	v_mfma_f32_16x16x32_bf16 v[124:127], v[180:183], v[196:199], v[124:127]
	v_mfma_f32_16x16x32_bf16 v[124:127], v[184:187], v[200:203], v[124:127]
	v_mfma_f32_16x16x32_bf16 v[116:119], v[188:191], v[196:199], v[116:119]
	v_mfma_f32_16x16x32_bf16 v[116:119], v[192:195], v[200:203], v[116:119]
	v_mfma_f32_16x16x32_bf16 v[108:111], v[180:183], v[222:225], v[108:111]
	v_mfma_f32_16x16x32_bf16 v[108:111], v[184:187], v[226:229], v[108:111]
	v_mfma_f32_16x16x32_bf16 v[100:103], v[188:191], v[222:225], v[100:103]
	v_mfma_f32_16x16x32_bf16 v[100:103], v[192:195], v[226:229], v[100:103]
	v_mfma_f32_16x16x32_bf16 v[90:93], v[180:183], v[230:233], v[90:93]
	v_mfma_f32_16x16x32_bf16 v[90:93], v[184:187], v[234:237], v[90:93]
	v_mfma_f32_16x16x32_bf16 v[82:85], v[188:191], v[230:233], v[82:85]
	v_mfma_f32_16x16x32_bf16 v[82:85], v[192:195], v[234:237], v[82:85]
	v_mfma_f32_16x16x32_bf16 v[74:77], v[180:183], v[238:241], v[74:77]
	v_mfma_f32_16x16x32_bf16 v[74:77], v[184:187], v[242:245], v[74:77]
	s_setprio 2
	s_barrier
; #define PG8_STAGE(bufoff, gbase, voff) do { _Pragma("unroll") for (int _i = 0; _i < 2; ++_i) \
;         __builtin_amdgcn_global_load_lds((const unsigned*)((const char*)(gbase) + (voff)[_i]), (PG8_LAS unsigned*)(lds + (bufoff) + ldsw + _i * 8192), 16, 0, AUX_A); } while (0)
; #define PG8_STAGEB(bufoff, gbase, voff) do { _Pragma("unroll") for (int _i = 0; _i < 2; ++_i) \
;         __builtin_amdgcn_global_load_lds((const unsigned*)((const char*)(gbase) + (voff)[_i]), (PG8_LAS unsigned*)(lds + (bufoff) + ldsw + _i * 8192), 16, 0, AUX_B); } while (0)
; #define PG8_LDA(dst, b, h) do { _Pragma("unroll") for (int m = 0; m < 4; ++m) _Pragma("unroll") for (int k = 0; k < 2; ++k) dst[m][k] = *(const PG8_LAS bf16x8*)(lds + PG8_SA(b, h) + aoff + m * 2048 + k * 1024); } while (0)
; #define PG8_MMA(ai, bj, At, Bt) do { __builtin_amdgcn_s_setprio(1); _Pragma("unroll") for (int m = 0; m < 4; ++m) _Pragma("unroll") for (int n = 0; n < 2; ++n) _Pragma("unroll") for (int k = 0; k < 2; ++k) \
;         acc[ai][bj][m][n] = __builtin_amdgcn_mfma_f32_16x16x32_bf16(Bt[n][k], At[m][k], acc[ai][bj][m][n], 0, 0, 0); __builtin_amdgcn_s_setprio(0); } while (0)
; #define PG8_WAIT_V(n) asm volatile("s_waitcnt vmcnt(" #n ")" ::: "memory")
; #define PG8_WAIT_L(n) asm volatile("s_waitcnt lgkmcnt(" #n ")" ::: "memory")
; #define PG8_BAR __builtin_amdgcn_s_barrier()
; #define PG8_SCHED __builtin_amdgcn_sched_barrier(0)
; template <class Epi, class Sched, bool ALIGN_EPI = false, bool SP2 = false>
; __device__ __forceinline__ void gemm_phase(PG8_LAS unsigned char* lds, const Gemm g, const Sched& S, const Epi& E) {
;     ...
;         for (int t = 0; t < nt; t += 2) {
;     ...
;             PG8_LDA(At, 1, 1); PG8_STAGEB(PG8_SB(1, 0), b3, voffB); PG8_STAGEB(PG8_SB(1, 1), b3 + hstep, voffB); PG8_STAGE(PG8_SA(1, 0), a3, voffA);
;             PG8_WAIT_V(8); PG8_WAIT_L(0); PG8_BAR; PG8_MMA(1, 0, At, B0); PG8_MMA(1, 1, At, B1); PG8_BAR; PG8_SCHED;
	v_mfma_f32_16x16x32_bf16 v[66:69], v[188:191], v[238:241], v[66:69]
	v_mfma_f32_16x16x32_bf16 v[66:69], v[192:195], v[242:245], v[66:69]
	s_setprio 0
	s_mov_b32 m0, s1
	v_lshl_add_u64 v[166:167], v[166:167], 0, s[76:77]
	ds_read_b128 v[196:199], v149 offset:49152
	ds_read_b128 v[200:203], v149 offset:50176
	ds_read_b128 v[222:225], v149 offset:51200
	ds_read_b128 v[226:229], v149 offset:52224
	ds_read_b128 v[230:233], v149 offset:53248
	ds_read_b128 v[234:237], v149 offset:54272
	ds_read_b128 v[238:241], v149 offset:55296
	ds_read_b128 v[242:245], v149 offset:56320
	global_load_lds_dwordx4 v[166:167], off
	v_lshl_add_u64 v[166:167], v[168:169], 0, s[76:77]
	s_mov_b32 m0, s0
	s_nop 0
	global_load_lds_dwordx4 v[166:167], off
	v_lshl_add_u64 v[166:167], s[36:37], 0, v[136:137]
	s_mov_b32 m0, s46
	s_nop 0
	global_load_lds_dwordx4 v[166:167], off
	v_lshl_add_u64 v[166:167], s[36:37], 0, v[132:133]
	s_mov_b32 m0, s31
	s_nop 0
	global_load_lds_dwordx4 v[166:167], off
	s_waitcnt vmcnt(6)
	s_waitcnt lgkmcnt(0)
	s_setprio 1
	s_barrier
	v_mfma_f32_16x16x32_bf16 v[62:65], v[150:153], v[196:199], v[62:65]
	v_mfma_f32_16x16x32_bf16 v[62:65], v[154:157], v[200:203], v[62:65]
	v_mfma_f32_16x16x32_bf16 v[54:57], v[158:161], v[196:199], v[54:57]
	v_mfma_f32_16x16x32_bf16 v[54:57], v[162:165], v[200:203], v[54:57]
	v_mfma_f32_16x16x32_bf16 v[46:49], v[150:153], v[222:225], v[46:49]
	v_mfma_f32_16x16x32_bf16 v[46:49], v[154:157], v[226:229], v[46:49]
	v_mfma_f32_16x16x32_bf16 v[38:41], v[158:161], v[222:225], v[38:41]
	v_mfma_f32_16x16x32_bf16 v[38:41], v[162:165], v[226:229], v[38:41]
	v_mfma_f32_16x16x32_bf16 v[30:33], v[150:153], v[230:233], v[30:33]
	v_mfma_f32_16x16x32_bf16 v[30:33], v[154:157], v[234:237], v[30:33]
	v_mfma_f32_16x16x32_bf16 v[22:25], v[158:161], v[230:233], v[22:25]
	v_mfma_f32_16x16x32_bf16 v[22:25], v[162:165], v[234:237], v[22:25]
	v_mfma_f32_16x16x32_bf16 v[14:17], v[150:153], v[238:241], v[14:17]
	v_mfma_f32_16x16x32_bf16 v[14:17], v[154:157], v[242:245], v[14:17]
	v_mfma_f32_16x16x32_bf16 v[6:9], v[158:161], v[238:241], v[6:9]
	v_mfma_f32_16x16x32_bf16 v[6:9], v[162:165], v[242:245], v[6:9]
	s_setprio 0
	s_setprio 1
	v_mfma_f32_16x16x32_bf16 v[58:61], v[180:183], v[196:199], v[58:61]
	v_mfma_f32_16x16x32_bf16 v[58:61], v[184:187], v[200:203], v[58:61]
	v_mfma_f32_16x16x32_bf16 v[50:53], v[188:191], v[196:199], v[50:53]
	v_mfma_f32_16x16x32_bf16 v[50:53], v[192:195], v[200:203], v[50:53]
	v_mfma_f32_16x16x32_bf16 v[42:45], v[180:183], v[222:225], v[42:45]
	v_mfma_f32_16x16x32_bf16 v[42:45], v[184:187], v[226:229], v[42:45]
	v_mfma_f32_16x16x32_bf16 v[34:37], v[188:191], v[222:225], v[34:37]
	v_mfma_f32_16x16x32_bf16 v[34:37], v[192:195], v[226:229], v[34:37]
	v_mfma_f32_16x16x32_bf16 v[26:29], v[180:183], v[230:233], v[26:29]
	v_mfma_f32_16x16x32_bf16 v[26:29], v[184:187], v[234:237], v[26:29]
	v_mfma_f32_16x16x32_bf16 v[18:21], v[188:191], v[230:233], v[18:21]
	v_mfma_f32_16x16x32_bf16 v[18:21], v[192:195], v[234:237], v[18:21]
	v_mfma_f32_16x16x32_bf16 v[10:13], v[180:183], v[238:241], v[10:13]
	v_mfma_f32_16x16x32_bf16 v[10:13], v[184:187], v[242:245], v[10:13]
	s_setprio 2
	s_barrier
	v_mfma_f32_16x16x32_bf16 v[2:5], v[188:191], v[238:241], v[2:5]
	v_mfma_f32_16x16x32_bf16 v[2:5], v[192:195], v[242:245], v[2:5]
	s_setprio 0
	v_lshl_add_u64 v[144:145], v[144:145], 0, s[86:87]
	v_lshl_add_u64 v[146:147], v[146:147], 0, s[86:87]
	s_cmp_gt_u32 s30, 31
	s_mov_b32 s29, s30
	s_cbranch_scc1 .Lpx_1458
